# speedup vs baseline: 1.0266x; 1.0004x over previous
.LBB0_409:
	v_mov_b32_e32 v126, v226
	s_lshl_b32 s58, s22, 8
	v_and_b32_e32 v127, 15, v126
	v_bfe_u32 v126, v126, 4, 2
	v_and_b32_e32 v202, 1, v126
	v_mul_u32_u24_e32 v204, 12, v202
	v_mul_u32_u24_e32 v202, 24, v202
	v_mov_b32_e32 v203, 0
	v_mov_b32_e32 v205, 0
	s_mov_b64 s[60:61], -1
	s_and_b64 vcc, exec, s[46:47]
	s_cbranch_vccz .LBB0_411
	s_ashr_i32 s59, s58, 31
	v_readlane_b32 s60, v251, 0
	s_lshl_b64 s[2:3], s[58:59], 13
	v_readlane_b32 s66, v251, 6
	v_readlane_b32 s61, v251, 1
	v_readlane_b32 s67, v251, 7
	s_add_u32 s66, s66, s2
	v_readlane_b32 s62, v251, 2
	v_readlane_b32 s63, v251, 3
	v_readlane_b32 s64, v251, 4
	v_readlane_b32 s65, v251, 5
	s_addc_u32 s67, s67, s3
	s_mov_b64 s[60:61], 0

.LBB0_416:
	v_readlane_b32 s2, v251, 22
	v_readlane_b32 s2, v251, 16
	v_readlane_b32 s3, v251, 17
	v_readlane_b32 s2, v254, 58
	v_readlane_b32 s3, v254, 59
	v_readlane_b32 s72, v251, 0
	s_lshl_b64 s[2:3], s[58:59], 11
	s_lshl_b64 s[60:61], s[58:59], 13
	v_readlane_b32 s78, v251, 6
	v_readlane_b32 s73, v251, 1
	v_readlane_b32 s79, v251, 7
	s_add_u32 s60, s78, s60
	s_addc_u32 s61, s79, s61
	s_lshl_b64 s[62:63], s[58:59], 12
	v_readlane_b32 s72, v253, 22
	v_readlane_b32 s73, v253, 23
	s_add_u32 s62, s72, s62
	s_addc_u32 s63, s73, s63
	s_lshl_b64 s[58:59], s[58:59], 7
	s_add_u32 s22, s64, s58
	s_addc_u32 s49, s65, s59
	s_lshl_b32 s58, s12, 2
	s_ashr_i32 s59, s58, 31
	s_lshl_b64 s[58:59], s[58:59], 2
	s_add_u32 s22, s22, s58
	s_addc_u32 s49, s49, s59
	s_add_u32 s58, s22, s13
	s_addc_u32 s59, s49, 0
	s_add_u32 s64, s81, s2
	v_readlane_b32 s2, v253, 39
	s_addc_u32 s65, s2, s3
	s_lshl_b32 s2, s12, 8
	s_or_b32 s2, s2, s40
	v_lshl_add_u32 v192, v126, 2, s2
	v_add_u32_e32 v210, s1, v127
	v_lshlrev_b32_e32 v127, 2, v127
	v_ashrrev_i32_e32 v193, 31, v192
	v_lshl_add_u32 v127, v126, 6, v127
	v_ashrrev_i32_e32 v211, 31, v210
	v_lshl_add_u64 v[208:209], v[192:193], 2, s[66:67]
	v_xor_b32_e32 v242, 64, v127
	v_xor_b32_e32 v241, 0x80, v127
	v_cmp_eq_u32_e32 vcc, 0, v126
	v_lshlrev_b64 v[126:127], 13, v[210:211]
	v_lshl_add_u64 v[126:127], v[208:209], 0, v[126:127]
	flat_load_dwordx4 v[194:197], v[126:127]
	flat_load_dwordx4 v[186:189], v[126:127] offset:64
	flat_load_dwordx4 v[182:185], v[126:127] offset:512
	flat_load_dwordx4 v[178:181], v[126:127] offset:576
	v_add_u32_e32 v216, 16, v210
	v_ashrrev_i32_e32 v217, 31, v216
	v_lshlrev_b64 v[126:127], 13, v[216:217]
	v_add_u32_e32 v214, 32, v210
	v_lshl_add_u64 v[126:127], v[208:209], 0, v[126:127]
	v_ashrrev_i32_e32 v215, 31, v214
	flat_load_dwordx4 v[174:177], v[126:127]
	flat_load_dwordx4 v[170:173], v[126:127] offset:64
	flat_load_dwordx4 v[166:169], v[126:127] offset:512
	flat_load_dwordx4 v[162:165], v[126:127] offset:576
	v_lshlrev_b64 v[126:127], 13, v[214:215]
	v_add_u32_e32 v212, 48, v210
	v_lshl_add_u64 v[126:127], v[208:209], 0, v[126:127]
	v_ashrrev_i32_e32 v213, 31, v212
	flat_load_dwordx4 v[158:161], v[126:127]
	flat_load_dwordx4 v[154:157], v[126:127] offset:64
	flat_load_dwordx4 v[150:153], v[126:127] offset:512
	flat_load_dwordx4 v[142:145], v[126:127] offset:576
	v_lshlrev_b64 v[126:127], 13, v[212:213]
	v_lshl_add_u64 v[126:127], v[208:209], 0, v[126:127]
	flat_load_dwordx4 v[146:149], v[126:127]
	flat_load_dwordx4 v[138:141], v[126:127] offset:64
	flat_load_dwordx4 v[134:137], v[126:127] offset:512
	s_nop 0
	flat_load_dwordx4 v[126:129], v[126:127] offset:576
	v_lshlrev_b64 v[198:199], 11, v[210:211]
	v_lshl_add_u64 v[198:199], v[198:199], 0, v[192:193]
	v_lshl_add_u64 v[222:223], v[198:199], 2, s[60:61]
	v_lshl_add_u64 v[220:221], v[198:199], 1, s[62:63]
	v_lshl_add_u64 v[218:219], s[64:65], 0, v[198:199]
	v_readlane_b32 s74, v251, 2
	v_readlane_b32 s75, v251, 3
	v_readlane_b32 s76, v251, 4
	v_readlane_b32 s77, v251, 5
	s_waitcnt vmcnt(0) lgkmcnt(0)
	v_pk_add_f32 v[132:133], v[132:133], v[196:197]
	v_pk_add_f32 v[130:131], v[130:131], v[194:195]
	v_mul_f32_e32 v195, v133, v133
	v_mul_f32_e32 v194, v131, v131
	v_fmac_f32_e32 v194, v130, v130
	v_fmac_f32_e32 v195, v132, v132
	global_store_dwordx4 v[222:223], v[130:133], off
	v_add_f32_e32 v196, v194, v195
	v_cvt_pk_bf16_f32 v194, v130, v131
	v_cvt_pk_bf16_f32 v195, v132, v133
	v_mov_b32_e32 v228, v194
	v_mov_b32_e32 v229, v195
	v_mov_b32_e32 v194, v1
	v_cvt_pk_fp8_f32 v194, v130, v131
	v_pk_add_f32 v[124:125], v[124:125], v[188:189]
	v_pk_add_f32 v[122:123], v[122:123], v[186:187]
	v_mul_f32_e32 v131, v125, v125
	v_cvt_pk_fp8_f32 v194, v132, v133 op_sel:[0,0,1]
	v_mul_f32_e32 v130, v123, v123
	v_fmac_f32_e32 v130, v122, v122
	v_fmac_f32_e32 v131, v124, v124
	v_add_f32_e32 v130, v130, v131
	v_mov_b32_e32 v244, v194
	global_store_dwordx4 v[222:223], v[122:125], off offset:64
	v_add_f32_e32 v132, v196, v130
	v_cvt_pk_bf16_f32 v130, v122, v123
	v_cvt_pk_bf16_f32 v131, v124, v125
	v_mov_b32_e32 v230, v130
	v_mov_b32_e32 v231, v131
	v_lshl_add_u64 v[236:237], v[220:221], 0, v[202:203]
	s_nop 0
	v_permlane16_swap_b32_e32 v228, v230
	v_permlane16_swap_b32_e32 v229, v231
	global_store_dwordx4 v[236:237], v[228:231], off
	s_nop 1
	v_mov_b32_e32 v130, v1
	v_cvt_pk_fp8_f32 v130, v122, v123
	v_pk_add_f32 v[120:121], v[120:121], v[184:185]
	v_pk_add_f32 v[118:119], v[118:119], v[182:183]
	v_mul_f32_e32 v123, v121, v121
	v_cvt_pk_fp8_f32 v130, v124, v125 op_sel:[0,0,1]
	v_mul_f32_e32 v122, v119, v119
	v_fmac_f32_e32 v122, v118, v118
	v_fmac_f32_e32 v123, v120, v120
	v_add_f32_e32 v122, v122, v123
	v_mov_b32_e32 v245, v130
	v_lshl_add_u64 v[238:239], v[218:219], 0, v[204:205]
	s_nop 0
	v_permlane16_swap_b32_e32 v244, v245
	global_store_dwordx2 v[238:239], v[244:245], off
	s_nop 0
	global_store_dwordx4 v[222:223], v[118:121], off offset:512
	v_add_f32_e32 v124, v132, v122
	v_cvt_pk_bf16_f32 v122, v118, v119
	v_cvt_pk_bf16_f32 v123, v120, v121
	v_mov_b32_e32 v232, v122
	v_mov_b32_e32 v233, v123
	v_mov_b32_e32 v122, v1
	v_cvt_pk_fp8_f32 v122, v118, v119
	v_pk_add_f32 v[116:117], v[116:117], v[180:181]
	v_pk_add_f32 v[114:115], v[114:115], v[178:179]
	v_mul_f32_e32 v119, v117, v117
	v_cvt_pk_fp8_f32 v122, v120, v121 op_sel:[0,0,1]
	v_mul_f32_e32 v118, v115, v115
	v_fmac_f32_e32 v118, v114, v114
	v_fmac_f32_e32 v119, v116, v116
	v_add_f32_e32 v118, v118, v119
	v_mov_b32_e32 v246, v122
	global_store_dwordx4 v[222:223], v[114:117], off offset:576
	v_add_f32_e32 v120, v124, v118
	v_cvt_pk_bf16_f32 v118, v114, v115
	v_cvt_pk_bf16_f32 v119, v116, v117
	v_mov_b32_e32 v234, v118
	v_mov_b32_e32 v235, v119
	v_lshl_add_u64 v[236:237], v[220:221], 0, v[202:203]
	s_nop 0
	v_permlane16_swap_b32_e32 v232, v234
	v_permlane16_swap_b32_e32 v233, v235
	global_store_dwordx4 v[236:237], v[232:235], off offset:256
	s_nop 1
	v_mov_b32_e32 v118, v1
	v_cvt_pk_fp8_f32 v118, v114, v115
	ds_bpermute_b32 v114, v242, v120
	v_cvt_pk_fp8_f32 v118, v116, v117 op_sel:[0,0,1]
	s_waitcnt lgkmcnt(0)
	v_add_f32_e32 v114, v120, v114
	ds_bpermute_b32 v115, v241, v114
	v_mov_b32_e32 v247, v118
	v_lshl_add_u64 v[238:239], v[218:219], 0, v[204:205]
	s_nop 0
	v_permlane16_swap_b32_e32 v246, v247
	global_store_dwordx2 v[238:239], v[246:247], off offset:128
	s_nop 0
	s_and_saveexec_b64 s[66:67], vcc
	s_cbranch_execz .LBB0_418
	v_lshlrev_b32_e32 v116, 5, v210
	v_ashrrev_i32_e32 v117, 31, v116
	v_lshl_add_u64 v[116:117], v[116:117], 2, s[58:59]
	s_waitcnt lgkmcnt(0)
	v_add_f32_e32 v114, v114, v115
	global_store_dword v[116:117], v114, off
.LBB0_418:
	s_or_b64 exec, exec, s[66:67]
	v_pk_add_f32 v[110:111], v[110:111], v[174:175]
	v_mov_b32_e32 v121, v1
	v_cvt_pk_fp8_f32 v121, v110, v111
	s_waitcnt lgkmcnt(0)
	v_lshlrev_b64 v[114:115], 11, v[216:217]
	v_lshl_add_u64 v[114:115], v[114:115], 0, v[192:193]
	v_pk_add_f32 v[112:113], v[112:113], v[176:177]
	v_lshl_add_u64 v[116:117], v[114:115], 2, s[60:61]
	v_mul_f32_e32 v120, v111, v111
	v_mul_f32_e32 v122, v113, v113
	global_store_dwordx4 v[116:117], v[110:113], off
	v_fmac_f32_e32 v120, v110, v110
	v_fmac_f32_e32 v122, v112, v112
	v_cvt_pk_fp8_f32 v121, v112, v113 op_sel:[0,0,1]
	v_cvt_pk_bf16_f32 v110, v110, v111
	v_cvt_pk_bf16_f32 v111, v112, v113
	v_pk_add_f32 v[106:107], v[106:107], v[170:171]
	v_mov_b32_e32 v112, v1
	v_cvt_pk_fp8_f32 v112, v106, v107
	v_pk_add_f32 v[108:109], v[108:109], v[172:173]
	v_lshl_add_u64 v[118:119], v[114:115], 1, s[62:63]
	v_lshl_add_u64 v[114:115], s[64:65], 0, v[114:115]
	v_cvt_pk_fp8_f32 v112, v108, v109 op_sel:[0,0,1]
	v_mov_b32_e32 v228, v110
	v_mov_b32_e32 v229, v111
	v_mov_b32_e32 v244, v121
	v_mul_f32_e32 v110, v107, v107
	global_store_dwordx4 v[116:117], v[106:109], off offset:64
	v_fmac_f32_e32 v110, v106, v106
	v_mul_f32_e32 v111, v109, v109
	v_cvt_pk_bf16_f32 v106, v106, v107
	v_cvt_pk_bf16_f32 v107, v108, v109
	v_pk_add_f32 v[104:105], v[104:105], v[168:169]
	v_pk_add_f32 v[102:103], v[102:103], v[166:167]
	v_fmac_f32_e32 v111, v108, v108
	v_mov_b32_e32 v230, v106
	v_mov_b32_e32 v231, v107
	v_lshl_add_u64 v[236:237], v[118:119], 0, v[202:203]
	s_nop 0
	v_permlane16_swap_b32_e32 v228, v230
	v_permlane16_swap_b32_e32 v229, v231
	global_store_dwordx4 v[236:237], v[228:231], off
	s_nop 1
	v_mov_b32_e32 v245, v112
	v_lshl_add_u64 v[238:239], v[114:115], 0, v[204:205]
	s_nop 0
	v_permlane16_swap_b32_e32 v244, v245
	global_store_dwordx2 v[238:239], v[244:245], off
	s_nop 0
	v_mul_f32_e32 v106, v103, v103
	v_mul_f32_e32 v107, v105, v105
	v_add_f32_e32 v120, v120, v122
	v_add_f32_e32 v110, v110, v111
	v_fmac_f32_e32 v106, v102, v102
	v_fmac_f32_e32 v107, v104, v104
	v_add_f32_e32 v110, v120, v110
	v_add_f32_e32 v106, v106, v107
	v_mov_b32_e32 v108, v1
	global_store_dwordx4 v[116:117], v[102:105], off offset:512
	v_cvt_pk_fp8_f32 v108, v102, v103
	v_add_f32_e32 v109, v110, v106
	v_cvt_pk_bf16_f32 v106, v102, v103
	v_pk_add_f32 v[102:103], v[100:101], v[164:165]
	v_pk_add_f32 v[100:101], v[98:99], v[162:163]
	v_mul_f32_e32 v99, v103, v103
	v_mul_f32_e32 v98, v101, v101
	v_fmac_f32_e32 v98, v100, v100
	v_fmac_f32_e32 v99, v102, v102
	v_add_f32_e32 v98, v98, v99
	v_add_f32_e32 v98, v109, v98
	ds_bpermute_b32 v99, v242, v98
	v_cvt_pk_bf16_f32 v107, v104, v105
	v_cvt_pk_fp8_f32 v108, v104, v105 op_sel:[0,0,1]
	v_mov_b32_e32 v104, v1
	v_cvt_pk_fp8_f32 v104, v100, v101
	s_waitcnt lgkmcnt(0)
	v_add_f32_e32 v98, v98, v99
	ds_bpermute_b32 v99, v241, v98
	v_mov_b32_e32 v232, v106
	v_mov_b32_e32 v233, v107
	v_mov_b32_e32 v246, v108
	global_store_dwordx4 v[116:117], v[100:103], off offset:576
	v_cvt_pk_fp8_f32 v104, v102, v103 op_sel:[0,0,1]
	s_nop 0
	v_cvt_pk_bf16_f32 v100, v100, v101
	v_cvt_pk_bf16_f32 v101, v102, v103
	v_mov_b32_e32 v234, v100
	v_mov_b32_e32 v235, v101
	v_lshl_add_u64 v[236:237], v[118:119], 0, v[202:203]
	s_nop 0
	v_permlane16_swap_b32_e32 v232, v234
	v_permlane16_swap_b32_e32 v233, v235
	global_store_dwordx4 v[236:237], v[232:235], off offset:256
	s_nop 1
	v_mov_b32_e32 v247, v104
	v_lshl_add_u64 v[238:239], v[114:115], 0, v[204:205]
	s_nop 0
	v_permlane16_swap_b32_e32 v246, v247
	global_store_dwordx2 v[238:239], v[246:247], off offset:128
	s_nop 0
	s_and_saveexec_b64 s[66:67], vcc
	s_cbranch_execz .LBB0_420
	v_lshlrev_b32_e32 v100, 5, v216
	v_ashrrev_i32_e32 v101, 31, v100
	v_lshl_add_u64 v[100:101], v[100:101], 2, s[58:59]
	s_waitcnt lgkmcnt(0)
	v_add_f32_e32 v98, v98, v99
	global_store_dword v[100:101], v98, off
.LBB0_420:
	s_or_b64 exec, exec, s[66:67]
	v_pk_add_f32 v[94:95], v[94:95], v[158:159]
	v_mov_b32_e32 v105, v1
	v_cvt_pk_fp8_f32 v105, v94, v95
	s_waitcnt lgkmcnt(0)
	v_lshlrev_b64 v[98:99], 11, v[214:215]
	v_lshl_add_u64 v[98:99], v[98:99], 0, v[192:193]
	v_pk_add_f32 v[96:97], v[96:97], v[160:161]
	v_lshl_add_u64 v[100:101], v[98:99], 2, s[60:61]
	v_mul_f32_e32 v104, v95, v95
	v_mul_f32_e32 v106, v97, v97
	global_store_dwordx4 v[100:101], v[94:97], off
	v_fmac_f32_e32 v104, v94, v94
	v_fmac_f32_e32 v106, v96, v96
	v_cvt_pk_fp8_f32 v105, v96, v97 op_sel:[0,0,1]
	v_cvt_pk_bf16_f32 v94, v94, v95
	v_cvt_pk_bf16_f32 v95, v96, v97
	v_pk_add_f32 v[90:91], v[90:91], v[154:155]
	v_mov_b32_e32 v96, v1
	v_cvt_pk_fp8_f32 v96, v90, v91
	v_pk_add_f32 v[92:93], v[92:93], v[156:157]
	v_lshl_add_u64 v[102:103], v[98:99], 1, s[62:63]
	v_lshl_add_u64 v[98:99], s[64:65], 0, v[98:99]
	v_cvt_pk_fp8_f32 v96, v92, v93 op_sel:[0,0,1]
	v_mov_b32_e32 v228, v94
	v_mov_b32_e32 v229, v95
	v_mov_b32_e32 v244, v105
	v_mul_f32_e32 v94, v91, v91
	global_store_dwordx4 v[100:101], v[90:93], off offset:64
	v_fmac_f32_e32 v94, v90, v90
	v_mul_f32_e32 v95, v93, v93
	v_cvt_pk_bf16_f32 v90, v90, v91
	v_cvt_pk_bf16_f32 v91, v92, v93
	v_pk_add_f32 v[88:89], v[88:89], v[152:153]
	v_pk_add_f32 v[86:87], v[86:87], v[150:151]
	v_fmac_f32_e32 v95, v92, v92
	v_mov_b32_e32 v230, v90
	v_mov_b32_e32 v231, v91
	v_lshl_add_u64 v[236:237], v[102:103], 0, v[202:203]
	s_nop 0
	v_permlane16_swap_b32_e32 v228, v230
	v_permlane16_swap_b32_e32 v229, v231
	global_store_dwordx4 v[236:237], v[228:231], off
	s_nop 1
	v_mov_b32_e32 v245, v96
	v_lshl_add_u64 v[238:239], v[98:99], 0, v[204:205]
	s_nop 0
	v_permlane16_swap_b32_e32 v244, v245
	global_store_dwordx2 v[238:239], v[244:245], off
	s_nop 0
	v_mul_f32_e32 v90, v87, v87
	v_mul_f32_e32 v91, v89, v89
	v_add_f32_e32 v104, v104, v106
	v_add_f32_e32 v94, v94, v95
	v_fmac_f32_e32 v90, v86, v86
	v_fmac_f32_e32 v91, v88, v88
	v_add_f32_e32 v94, v104, v94
	v_add_f32_e32 v90, v90, v91
	v_mov_b32_e32 v92, v1
	global_store_dwordx4 v[100:101], v[86:89], off offset:512
	v_cvt_pk_fp8_f32 v92, v86, v87
	v_add_f32_e32 v93, v94, v90
	v_cvt_pk_bf16_f32 v90, v86, v87
	v_pk_add_f32 v[86:87], v[84:85], v[144:145]
	v_pk_add_f32 v[84:85], v[82:83], v[142:143]
	v_mul_f32_e32 v83, v87, v87
	v_mul_f32_e32 v82, v85, v85
	v_fmac_f32_e32 v82, v84, v84
	v_fmac_f32_e32 v83, v86, v86
	v_add_f32_e32 v82, v82, v83
	v_add_f32_e32 v82, v93, v82
	ds_bpermute_b32 v83, v242, v82
	v_cvt_pk_bf16_f32 v91, v88, v89
	v_cvt_pk_fp8_f32 v92, v88, v89 op_sel:[0,0,1]
	v_mov_b32_e32 v88, v1
	v_cvt_pk_fp8_f32 v88, v84, v85
	s_waitcnt lgkmcnt(0)
	v_add_f32_e32 v82, v82, v83
	ds_bpermute_b32 v83, v241, v82
	v_mov_b32_e32 v232, v90
	v_mov_b32_e32 v233, v91
	v_mov_b32_e32 v246, v92
	global_store_dwordx4 v[100:101], v[84:87], off offset:576
	v_cvt_pk_fp8_f32 v88, v86, v87 op_sel:[0,0,1]
	s_nop 0
	v_cvt_pk_bf16_f32 v84, v84, v85
	v_cvt_pk_bf16_f32 v85, v86, v87
	v_mov_b32_e32 v234, v84
	v_mov_b32_e32 v235, v85
	v_lshl_add_u64 v[236:237], v[102:103], 0, v[202:203]
	s_nop 0
	v_permlane16_swap_b32_e32 v232, v234
	v_permlane16_swap_b32_e32 v233, v235
	global_store_dwordx4 v[236:237], v[232:235], off offset:256
	s_nop 1
	v_mov_b32_e32 v247, v88
	v_lshl_add_u64 v[238:239], v[98:99], 0, v[204:205]
	s_nop 0
	v_permlane16_swap_b32_e32 v246, v247
	global_store_dwordx2 v[238:239], v[246:247], off offset:128
	s_nop 0
	s_and_saveexec_b64 s[66:67], vcc
	s_cbranch_execz .LBB0_422
	v_lshlrev_b32_e32 v84, 5, v214
	v_ashrrev_i32_e32 v85, 31, v84
	v_lshl_add_u64 v[84:85], v[84:85], 2, s[58:59]
	s_waitcnt lgkmcnt(0)
	v_add_f32_e32 v82, v82, v83
	global_store_dword v[84:85], v82, off
.LBB0_422:
	s_or_b64 exec, exec, s[66:67]
	v_pk_add_f32 v[78:79], v[78:79], v[146:147]
	v_mov_b32_e32 v89, v1
	v_cvt_pk_fp8_f32 v89, v78, v79
	s_waitcnt lgkmcnt(0)
	v_lshlrev_b64 v[82:83], 11, v[212:213]
	v_lshl_add_u64 v[82:83], v[82:83], 0, v[192:193]
	v_pk_add_f32 v[80:81], v[80:81], v[148:149]
	v_lshl_add_u64 v[84:85], v[82:83], 2, s[60:61]
	v_mul_f32_e32 v88, v79, v79
	v_mul_f32_e32 v90, v81, v81
	global_store_dwordx4 v[84:85], v[78:81], off
	v_fmac_f32_e32 v88, v78, v78
	v_fmac_f32_e32 v90, v80, v80
	v_cvt_pk_fp8_f32 v89, v80, v81 op_sel:[0,0,1]
	v_cvt_pk_bf16_f32 v78, v78, v79
	v_cvt_pk_bf16_f32 v79, v80, v81
	v_pk_add_f32 v[74:75], v[74:75], v[138:139]
	v_mov_b32_e32 v80, v1
	v_cvt_pk_fp8_f32 v80, v74, v75
	v_pk_add_f32 v[76:77], v[76:77], v[140:141]
	v_lshl_add_u64 v[86:87], v[82:83], 1, s[62:63]
	v_lshl_add_u64 v[82:83], s[64:65], 0, v[82:83]
	v_cvt_pk_fp8_f32 v80, v76, v77 op_sel:[0,0,1]
	v_mov_b32_e32 v228, v78
	v_mov_b32_e32 v229, v79
	v_mov_b32_e32 v244, v89
	v_mul_f32_e32 v78, v75, v75
	global_store_dwordx4 v[84:85], v[74:77], off offset:64
	v_fmac_f32_e32 v78, v74, v74
	v_mul_f32_e32 v79, v77, v77
	v_cvt_pk_bf16_f32 v74, v74, v75
	v_cvt_pk_bf16_f32 v75, v76, v77
	v_pk_add_f32 v[72:73], v[72:73], v[136:137]
	v_pk_add_f32 v[70:71], v[70:71], v[134:135]
	v_fmac_f32_e32 v79, v76, v76
	v_mov_b32_e32 v230, v74
	v_mov_b32_e32 v231, v75
	v_lshl_add_u64 v[236:237], v[86:87], 0, v[202:203]
	s_nop 0
	v_permlane16_swap_b32_e32 v228, v230
	v_permlane16_swap_b32_e32 v229, v231
	global_store_dwordx4 v[236:237], v[228:231], off
	s_nop 1
	v_mov_b32_e32 v245, v80
	v_lshl_add_u64 v[238:239], v[82:83], 0, v[204:205]
	s_nop 0
	v_permlane16_swap_b32_e32 v244, v245
	global_store_dwordx2 v[238:239], v[244:245], off
	s_nop 0
	v_mul_f32_e32 v74, v71, v71
	v_mul_f32_e32 v75, v73, v73
	v_add_f32_e32 v88, v88, v90
	v_add_f32_e32 v78, v78, v79
	v_fmac_f32_e32 v74, v70, v70
	v_fmac_f32_e32 v75, v72, v72
	v_add_f32_e32 v78, v88, v78
	v_add_f32_e32 v74, v74, v75
	v_mov_b32_e32 v76, v1
	global_store_dwordx4 v[84:85], v[70:73], off offset:512
	v_cvt_pk_fp8_f32 v76, v70, v71
	v_add_f32_e32 v77, v78, v74
	v_cvt_pk_bf16_f32 v74, v70, v71
	v_pk_add_f32 v[70:71], v[68:69], v[128:129]
	v_pk_add_f32 v[68:69], v[66:67], v[126:127]
	v_mul_f32_e32 v67, v71, v71
	v_mul_f32_e32 v66, v69, v69
	v_fmac_f32_e32 v66, v68, v68
	v_fmac_f32_e32 v67, v70, v70
	v_add_f32_e32 v66, v66, v67
	v_add_f32_e32 v66, v77, v66
	ds_bpermute_b32 v67, v242, v66
	v_cvt_pk_bf16_f32 v75, v72, v73
	v_cvt_pk_fp8_f32 v76, v72, v73 op_sel:[0,0,1]
	v_mov_b32_e32 v72, v1
	v_cvt_pk_fp8_f32 v72, v68, v69
	s_waitcnt lgkmcnt(0)
	v_add_f32_e32 v66, v66, v67
	ds_bpermute_b32 v67, v241, v66
	v_mov_b32_e32 v232, v74
	v_mov_b32_e32 v233, v75
	v_mov_b32_e32 v246, v76
	global_store_dwordx4 v[84:85], v[68:71], off offset:576
	v_cvt_pk_fp8_f32 v72, v70, v71 op_sel:[0,0,1]
	s_nop 0
	v_cvt_pk_bf16_f32 v68, v68, v69
	v_cvt_pk_bf16_f32 v69, v70, v71
	v_mov_b32_e32 v234, v68
	v_mov_b32_e32 v235, v69
	v_lshl_add_u64 v[236:237], v[86:87], 0, v[202:203]
	s_nop 0
	v_permlane16_swap_b32_e32 v232, v234
	v_permlane16_swap_b32_e32 v233, v235
	global_store_dwordx4 v[236:237], v[232:235], off offset:256
	s_nop 1
	v_mov_b32_e32 v247, v72
	v_lshl_add_u64 v[238:239], v[82:83], 0, v[204:205]
	s_nop 0
	v_permlane16_swap_b32_e32 v246, v247
	global_store_dwordx2 v[238:239], v[246:247], off offset:128
	s_nop 0
	s_and_saveexec_b64 s[66:67], vcc
	s_cbranch_execz .LBB0_424
	v_lshlrev_b32_e32 v68, 5, v212
	v_ashrrev_i32_e32 v69, 31, v68
	v_lshl_add_u64 v[68:69], v[68:69], 2, s[58:59]
	s_waitcnt lgkmcnt(0)
	v_add_f32_e32 v66, v66, v67
	global_store_dword v[68:69], v66, off
.LBB0_424:
	s_or_b64 exec, exec, s[66:67]
	v_add_u32_e32 v128, 0x80, v210
	v_ashrrev_i32_e32 v129, 31, v128
	s_waitcnt lgkmcnt(0)
	v_lshlrev_b64 v[66:67], 13, v[128:129]
	v_lshl_add_u64 v[66:67], v[208:209], 0, v[66:67]
	flat_load_dwordx4 v[136:139], v[66:67]
	flat_load_dwordx4 v[140:143], v[66:67] offset:64
	flat_load_dwordx4 v[118:121], v[66:67] offset:512
	flat_load_dwordx4 v[114:117], v[66:67] offset:576
	v_add_u32_e32 v126, 0x90, v210
	v_ashrrev_i32_e32 v127, 31, v126
	v_lshlrev_b64 v[66:67], 13, v[126:127]
	v_add_u32_e32 v124, 0xa0, v210
	v_lshl_add_u64 v[66:67], v[208:209], 0, v[66:67]
	v_ashrrev_i32_e32 v125, 31, v124
	flat_load_dwordx4 v[110:113], v[66:67]
	flat_load_dwordx4 v[106:109], v[66:67] offset:64
	flat_load_dwordx4 v[102:105], v[66:67] offset:512
	flat_load_dwordx4 v[98:101], v[66:67] offset:576
	v_lshlrev_b64 v[66:67], 13, v[124:125]
	v_add_u32_e32 v122, 0xb0, v210
	v_lshl_add_u64 v[66:67], v[208:209], 0, v[66:67]
	v_ashrrev_i32_e32 v123, 31, v122
	flat_load_dwordx4 v[94:97], v[66:67]
	flat_load_dwordx4 v[90:93], v[66:67] offset:64
	flat_load_dwordx4 v[86:89], v[66:67] offset:512
	flat_load_dwordx4 v[78:81], v[66:67] offset:576
	v_lshlrev_b64 v[66:67], 13, v[122:123]
	v_lshl_add_u64 v[66:67], v[208:209], 0, v[66:67]
	flat_load_dwordx4 v[82:85], v[66:67]
	flat_load_dwordx4 v[74:77], v[66:67] offset:64
	flat_load_dwordx4 v[70:73], v[66:67] offset:512
	s_nop 0
	flat_load_dwordx4 v[66:69], v[66:67] offset:576
	v_lshlrev_b64 v[130:131], 11, v[128:129]
	v_lshl_add_u64 v[130:131], v[130:131], 0, v[192:193]
	v_lshl_add_u64 v[134:135], v[130:131], 2, s[60:61]
	v_lshl_add_u64 v[132:133], v[130:131], 1, s[62:63]
	v_lshl_add_u64 v[130:131], s[64:65], 0, v[130:131]
	s_waitcnt vmcnt(0) lgkmcnt(0)
	v_pk_add_f32 v[64:65], v[64:65], v[138:139]
	v_pk_add_f32 v[62:63], v[62:63], v[136:137]
	v_mul_f32_e32 v136, v65, v65
	v_mul_f32_e32 v129, v63, v63
	v_fmac_f32_e32 v129, v62, v62
	v_fmac_f32_e32 v136, v64, v64
	global_store_dwordx4 v[134:135], v[62:65], off
	v_add_f32_e32 v129, v129, v136
	v_cvt_pk_bf16_f32 v136, v62, v63
	v_cvt_pk_bf16_f32 v137, v64, v65
	v_mov_b32_e32 v228, v136
	v_mov_b32_e32 v229, v137
	v_mov_b32_e32 v136, v1
	v_cvt_pk_fp8_f32 v136, v62, v63
	v_pk_add_f32 v[60:61], v[60:61], v[142:143]
	v_pk_add_f32 v[58:59], v[58:59], v[140:141]
	v_mul_f32_e32 v63, v61, v61
	v_cvt_pk_fp8_f32 v136, v64, v65 op_sel:[0,0,1]
	v_mul_f32_e32 v62, v59, v59
	v_fmac_f32_e32 v62, v58, v58
	v_fmac_f32_e32 v63, v60, v60
	v_add_f32_e32 v62, v62, v63
	v_mov_b32_e32 v244, v136
	global_store_dwordx4 v[134:135], v[58:61], off offset:64
	v_add_f32_e32 v64, v129, v62
	v_cvt_pk_bf16_f32 v62, v58, v59
	v_cvt_pk_bf16_f32 v63, v60, v61
	v_mov_b32_e32 v230, v62
	v_mov_b32_e32 v231, v63
	v_lshl_add_u64 v[236:237], v[132:133], 0, v[202:203]
	s_nop 0
	v_permlane16_swap_b32_e32 v228, v230
	v_permlane16_swap_b32_e32 v229, v231
	global_store_dwordx4 v[236:237], v[228:231], off
	s_nop 1
	v_mov_b32_e32 v62, v1
	v_cvt_pk_fp8_f32 v62, v58, v59
	v_pk_add_f32 v[56:57], v[56:57], v[120:121]
	v_pk_add_f32 v[54:55], v[54:55], v[118:119]
	v_mul_f32_e32 v59, v57, v57
	v_cvt_pk_fp8_f32 v62, v60, v61 op_sel:[0,0,1]
	v_mul_f32_e32 v58, v55, v55
	v_fmac_f32_e32 v58, v54, v54
	v_fmac_f32_e32 v59, v56, v56
	v_add_f32_e32 v58, v58, v59
	v_mov_b32_e32 v245, v62
	v_lshl_add_u64 v[238:239], v[130:131], 0, v[204:205]
	s_nop 0
	v_permlane16_swap_b32_e32 v244, v245
	global_store_dwordx2 v[238:239], v[244:245], off
	s_nop 0
	global_store_dwordx4 v[134:135], v[54:57], off offset:512
	v_add_f32_e32 v60, v64, v58
	v_cvt_pk_bf16_f32 v58, v54, v55
	v_cvt_pk_bf16_f32 v59, v56, v57
	v_mov_b32_e32 v232, v58
	v_mov_b32_e32 v233, v59
	v_mov_b32_e32 v58, v1
	v_cvt_pk_fp8_f32 v58, v54, v55
	v_pk_add_f32 v[52:53], v[52:53], v[116:117]
	v_pk_add_f32 v[50:51], v[50:51], v[114:115]
	v_mul_f32_e32 v55, v53, v53
	v_cvt_pk_fp8_f32 v58, v56, v57 op_sel:[0,0,1]
	v_mul_f32_e32 v54, v51, v51
	v_fmac_f32_e32 v54, v50, v50
	v_fmac_f32_e32 v55, v52, v52
	v_add_f32_e32 v54, v54, v55
	v_mov_b32_e32 v246, v58
	global_store_dwordx4 v[134:135], v[50:53], off offset:576
	v_add_f32_e32 v56, v60, v54
	v_cvt_pk_bf16_f32 v54, v50, v51
	v_cvt_pk_bf16_f32 v55, v52, v53
	v_mov_b32_e32 v234, v54
	v_mov_b32_e32 v235, v55
	v_lshl_add_u64 v[236:237], v[132:133], 0, v[202:203]
	s_nop 0
	v_permlane16_swap_b32_e32 v232, v234
	v_permlane16_swap_b32_e32 v233, v235
	global_store_dwordx4 v[236:237], v[232:235], off offset:256
	s_nop 1
	v_mov_b32_e32 v54, v1
	v_cvt_pk_fp8_f32 v54, v50, v51
	ds_bpermute_b32 v50, v242, v56
	v_cvt_pk_fp8_f32 v54, v52, v53 op_sel:[0,0,1]
	s_waitcnt lgkmcnt(0)
	v_add_f32_e32 v50, v56, v50
	ds_bpermute_b32 v51, v241, v50
	v_mov_b32_e32 v247, v54
	v_lshl_add_u64 v[238:239], v[130:131], 0, v[204:205]
	s_nop 0
	v_permlane16_swap_b32_e32 v246, v247
	global_store_dwordx2 v[238:239], v[246:247], off offset:128
	s_nop 0
	s_and_saveexec_b64 s[66:67], vcc
	s_cbranch_execz .LBB0_426
	v_lshlrev_b32_e32 v52, 5, v128
	v_ashrrev_i32_e32 v53, 31, v52
	v_lshl_add_u64 v[52:53], v[52:53], 2, s[58:59]
	s_waitcnt lgkmcnt(0)
	v_add_f32_e32 v50, v50, v51
	global_store_dword v[52:53], v50, off
.LBB0_426:
	s_or_b64 exec, exec, s[66:67]
	v_pk_add_f32 v[46:47], v[46:47], v[110:111]
	v_mov_b32_e32 v57, v1
	v_cvt_pk_fp8_f32 v57, v46, v47
	s_waitcnt lgkmcnt(0)
	v_lshlrev_b64 v[50:51], 11, v[126:127]
	v_lshl_add_u64 v[50:51], v[50:51], 0, v[192:193]
	v_pk_add_f32 v[48:49], v[48:49], v[112:113]
	v_lshl_add_u64 v[52:53], v[50:51], 2, s[60:61]
	v_mul_f32_e32 v56, v47, v47
	v_mul_f32_e32 v58, v49, v49
	global_store_dwordx4 v[52:53], v[46:49], off
	v_fmac_f32_e32 v56, v46, v46
	v_fmac_f32_e32 v58, v48, v48
	v_cvt_pk_fp8_f32 v57, v48, v49 op_sel:[0,0,1]
	v_cvt_pk_bf16_f32 v46, v46, v47
	v_cvt_pk_bf16_f32 v47, v48, v49
	v_pk_add_f32 v[42:43], v[42:43], v[106:107]
	v_mov_b32_e32 v48, v1
	v_cvt_pk_fp8_f32 v48, v42, v43
	v_pk_add_f32 v[44:45], v[44:45], v[108:109]
	v_lshl_add_u64 v[54:55], v[50:51], 1, s[62:63]
	v_lshl_add_u64 v[50:51], s[64:65], 0, v[50:51]
	v_cvt_pk_fp8_f32 v48, v44, v45 op_sel:[0,0,1]
	v_mov_b32_e32 v228, v46
	v_mov_b32_e32 v229, v47
	v_mov_b32_e32 v244, v57
	v_mul_f32_e32 v46, v43, v43
	global_store_dwordx4 v[52:53], v[42:45], off offset:64
	v_fmac_f32_e32 v46, v42, v42
	v_mul_f32_e32 v47, v45, v45
	v_cvt_pk_bf16_f32 v42, v42, v43
	v_cvt_pk_bf16_f32 v43, v44, v45
	v_pk_add_f32 v[40:41], v[40:41], v[104:105]
	v_pk_add_f32 v[38:39], v[38:39], v[102:103]
	v_fmac_f32_e32 v47, v44, v44
	v_mov_b32_e32 v230, v42
	v_mov_b32_e32 v231, v43
	v_lshl_add_u64 v[236:237], v[54:55], 0, v[202:203]
	s_nop 0
	v_permlane16_swap_b32_e32 v228, v230
	v_permlane16_swap_b32_e32 v229, v231
	global_store_dwordx4 v[236:237], v[228:231], off
	s_nop 1
	v_mov_b32_e32 v245, v48
	v_lshl_add_u64 v[238:239], v[50:51], 0, v[204:205]
	s_nop 0
	v_permlane16_swap_b32_e32 v244, v245
	global_store_dwordx2 v[238:239], v[244:245], off
	s_nop 0
	v_mul_f32_e32 v42, v39, v39
	v_mul_f32_e32 v43, v41, v41
	v_add_f32_e32 v56, v56, v58
	v_add_f32_e32 v46, v46, v47
	v_fmac_f32_e32 v42, v38, v38
	v_fmac_f32_e32 v43, v40, v40
	v_add_f32_e32 v46, v56, v46
	v_add_f32_e32 v42, v42, v43
	v_mov_b32_e32 v44, v1
	global_store_dwordx4 v[52:53], v[38:41], off offset:512
	v_cvt_pk_fp8_f32 v44, v38, v39
	v_add_f32_e32 v45, v46, v42
	v_cvt_pk_bf16_f32 v42, v38, v39
	v_pk_add_f32 v[38:39], v[36:37], v[100:101]
	v_pk_add_f32 v[36:37], v[34:35], v[98:99]
	v_mul_f32_e32 v35, v39, v39
	v_mul_f32_e32 v34, v37, v37
	v_fmac_f32_e32 v34, v36, v36
	v_fmac_f32_e32 v35, v38, v38
	v_add_f32_e32 v34, v34, v35
	v_add_f32_e32 v34, v45, v34
	ds_bpermute_b32 v35, v242, v34
	v_cvt_pk_bf16_f32 v43, v40, v41
	v_cvt_pk_fp8_f32 v44, v40, v41 op_sel:[0,0,1]
	v_mov_b32_e32 v40, v1
	v_cvt_pk_fp8_f32 v40, v36, v37
	s_waitcnt lgkmcnt(0)
	v_add_f32_e32 v34, v34, v35
	ds_bpermute_b32 v35, v241, v34
	v_mov_b32_e32 v232, v42
	v_mov_b32_e32 v233, v43
	v_mov_b32_e32 v246, v44
	global_store_dwordx4 v[52:53], v[36:39], off offset:576
	v_cvt_pk_fp8_f32 v40, v38, v39 op_sel:[0,0,1]
	s_nop 0
	v_cvt_pk_bf16_f32 v36, v36, v37
	v_cvt_pk_bf16_f32 v37, v38, v39
	v_mov_b32_e32 v234, v36
	v_mov_b32_e32 v235, v37
	v_lshl_add_u64 v[236:237], v[54:55], 0, v[202:203]
	s_nop 0
	v_permlane16_swap_b32_e32 v232, v234
	v_permlane16_swap_b32_e32 v233, v235
	global_store_dwordx4 v[236:237], v[232:235], off offset:256
	s_nop 1
	v_mov_b32_e32 v247, v40
	v_lshl_add_u64 v[238:239], v[50:51], 0, v[204:205]
	s_nop 0
	v_permlane16_swap_b32_e32 v246, v247
	global_store_dwordx2 v[238:239], v[246:247], off offset:128
	s_nop 0
	s_and_saveexec_b64 s[66:67], vcc
	s_cbranch_execz .LBB0_428
	v_lshlrev_b32_e32 v36, 5, v126
	v_ashrrev_i32_e32 v37, 31, v36
	v_lshl_add_u64 v[36:37], v[36:37], 2, s[58:59]
	s_waitcnt lgkmcnt(0)
	v_add_f32_e32 v34, v34, v35
	global_store_dword v[36:37], v34, off
.LBB0_428:
	s_or_b64 exec, exec, s[66:67]
	v_pk_add_f32 v[30:31], v[30:31], v[94:95]
	v_mov_b32_e32 v41, v1
	v_cvt_pk_fp8_f32 v41, v30, v31
	s_waitcnt lgkmcnt(0)
	v_lshlrev_b64 v[34:35], 11, v[124:125]
	v_lshl_add_u64 v[34:35], v[34:35], 0, v[192:193]
	v_pk_add_f32 v[32:33], v[32:33], v[96:97]
	v_lshl_add_u64 v[36:37], v[34:35], 2, s[60:61]
	v_mul_f32_e32 v40, v31, v31
	v_mul_f32_e32 v42, v33, v33
	global_store_dwordx4 v[36:37], v[30:33], off
	v_fmac_f32_e32 v40, v30, v30
	v_fmac_f32_e32 v42, v32, v32
	v_cvt_pk_fp8_f32 v41, v32, v33 op_sel:[0,0,1]
	v_cvt_pk_bf16_f32 v30, v30, v31
	v_cvt_pk_bf16_f32 v31, v32, v33
	v_pk_add_f32 v[26:27], v[26:27], v[90:91]
	v_mov_b32_e32 v32, v1
	v_cvt_pk_fp8_f32 v32, v26, v27
	v_pk_add_f32 v[28:29], v[28:29], v[92:93]
	v_lshl_add_u64 v[38:39], v[34:35], 1, s[62:63]
	v_lshl_add_u64 v[34:35], s[64:65], 0, v[34:35]
	v_cvt_pk_fp8_f32 v32, v28, v29 op_sel:[0,0,1]
	v_mov_b32_e32 v228, v30
	v_mov_b32_e32 v229, v31
	v_mov_b32_e32 v244, v41
	v_mul_f32_e32 v30, v27, v27
	global_store_dwordx4 v[36:37], v[26:29], off offset:64
	v_fmac_f32_e32 v30, v26, v26
	v_mul_f32_e32 v31, v29, v29
	v_cvt_pk_bf16_f32 v26, v26, v27
	v_cvt_pk_bf16_f32 v27, v28, v29
	v_pk_add_f32 v[24:25], v[24:25], v[88:89]
	v_pk_add_f32 v[22:23], v[22:23], v[86:87]
	v_fmac_f32_e32 v31, v28, v28
	v_mov_b32_e32 v230, v26
	v_mov_b32_e32 v231, v27
	v_lshl_add_u64 v[236:237], v[38:39], 0, v[202:203]
	s_nop 0
	v_permlane16_swap_b32_e32 v228, v230
	v_permlane16_swap_b32_e32 v229, v231
	global_store_dwordx4 v[236:237], v[228:231], off
	s_nop 1
	v_mov_b32_e32 v245, v32
	v_lshl_add_u64 v[238:239], v[34:35], 0, v[204:205]
	s_nop 0
	v_permlane16_swap_b32_e32 v244, v245
	global_store_dwordx2 v[238:239], v[244:245], off
	s_nop 0
	v_mul_f32_e32 v26, v23, v23
	v_mul_f32_e32 v27, v25, v25
	v_add_f32_e32 v40, v40, v42
	v_add_f32_e32 v30, v30, v31
	v_fmac_f32_e32 v26, v22, v22
	v_fmac_f32_e32 v27, v24, v24
	v_add_f32_e32 v30, v40, v30
	v_add_f32_e32 v26, v26, v27
	v_mov_b32_e32 v28, v1
	global_store_dwordx4 v[36:37], v[22:25], off offset:512
	v_cvt_pk_fp8_f32 v28, v22, v23
	v_add_f32_e32 v29, v30, v26
	v_cvt_pk_bf16_f32 v26, v22, v23
	v_pk_add_f32 v[22:23], v[20:21], v[80:81]
	v_pk_add_f32 v[20:21], v[18:19], v[78:79]
	v_mul_f32_e32 v19, v23, v23
	v_mul_f32_e32 v18, v21, v21
	v_fmac_f32_e32 v18, v20, v20
	v_fmac_f32_e32 v19, v22, v22
	v_add_f32_e32 v18, v18, v19
	v_add_f32_e32 v18, v29, v18
	ds_bpermute_b32 v19, v242, v18
	v_cvt_pk_bf16_f32 v27, v24, v25
	v_cvt_pk_fp8_f32 v28, v24, v25 op_sel:[0,0,1]
	v_mov_b32_e32 v24, v1
	v_cvt_pk_fp8_f32 v24, v20, v21
	s_waitcnt lgkmcnt(0)
	v_add_f32_e32 v18, v18, v19
	ds_bpermute_b32 v19, v241, v18
	v_mov_b32_e32 v232, v26
	v_mov_b32_e32 v233, v27
	v_mov_b32_e32 v246, v28
	global_store_dwordx4 v[36:37], v[20:23], off offset:576
	v_cvt_pk_fp8_f32 v24, v22, v23 op_sel:[0,0,1]
	s_nop 0
	v_cvt_pk_bf16_f32 v20, v20, v21
	v_cvt_pk_bf16_f32 v21, v22, v23
	v_mov_b32_e32 v234, v20
	v_mov_b32_e32 v235, v21
	v_lshl_add_u64 v[236:237], v[38:39], 0, v[202:203]
	s_nop 0
	v_permlane16_swap_b32_e32 v232, v234
	v_permlane16_swap_b32_e32 v233, v235
	global_store_dwordx4 v[236:237], v[232:235], off offset:256
	s_nop 1
	v_mov_b32_e32 v247, v24
	v_lshl_add_u64 v[238:239], v[34:35], 0, v[204:205]
	s_nop 0
	v_permlane16_swap_b32_e32 v246, v247
	global_store_dwordx2 v[238:239], v[246:247], off offset:128
	s_nop 0
	s_and_saveexec_b64 s[66:67], vcc
	s_cbranch_execz .LBB0_430
	v_lshlrev_b32_e32 v20, 5, v124
	v_ashrrev_i32_e32 v21, 31, v20
	v_lshl_add_u64 v[20:21], v[20:21], 2, s[58:59]
	s_waitcnt lgkmcnt(0)
	v_add_f32_e32 v18, v18, v19
	global_store_dword v[20:21], v18, off
.LBB0_430:
	s_or_b64 exec, exec, s[66:67]
	v_pk_add_f32 v[14:15], v[14:15], v[82:83]
	v_mov_b32_e32 v25, v1
	v_cvt_pk_fp8_f32 v25, v14, v15
	s_waitcnt lgkmcnt(0)
	v_lshlrev_b64 v[18:19], 11, v[122:123]
	v_lshl_add_u64 v[18:19], v[18:19], 0, v[192:193]
	v_pk_add_f32 v[16:17], v[16:17], v[84:85]
	v_lshl_add_u64 v[20:21], v[18:19], 2, s[60:61]
	v_mul_f32_e32 v24, v15, v15
	v_mul_f32_e32 v26, v17, v17
	global_store_dwordx4 v[20:21], v[14:17], off
	v_fmac_f32_e32 v24, v14, v14
	v_fmac_f32_e32 v26, v16, v16
	v_cvt_pk_fp8_f32 v25, v16, v17 op_sel:[0,0,1]
	v_cvt_pk_bf16_f32 v14, v14, v15
	v_cvt_pk_bf16_f32 v15, v16, v17
	v_pk_add_f32 v[10:11], v[10:11], v[74:75]
	v_mov_b32_e32 v16, v1
	v_cvt_pk_fp8_f32 v16, v10, v11
	v_pk_add_f32 v[12:13], v[12:13], v[76:77]
	v_lshl_add_u64 v[22:23], v[18:19], 1, s[62:63]
	v_lshl_add_u64 v[18:19], s[64:65], 0, v[18:19]
	v_cvt_pk_fp8_f32 v16, v12, v13 op_sel:[0,0,1]
	v_mov_b32_e32 v228, v14
	v_mov_b32_e32 v229, v15
	v_mov_b32_e32 v244, v25
	v_mul_f32_e32 v14, v11, v11
	global_store_dwordx4 v[20:21], v[10:13], off offset:64
	v_fmac_f32_e32 v14, v10, v10
	v_mul_f32_e32 v15, v13, v13
	v_cvt_pk_bf16_f32 v10, v10, v11
	v_cvt_pk_bf16_f32 v11, v12, v13
	v_pk_add_f32 v[8:9], v[8:9], v[72:73]
	v_pk_add_f32 v[6:7], v[6:7], v[70:71]
	v_fmac_f32_e32 v15, v12, v12
	v_mov_b32_e32 v230, v10
	v_mov_b32_e32 v231, v11
	v_lshl_add_u64 v[236:237], v[22:23], 0, v[202:203]
	s_nop 0
	v_permlane16_swap_b32_e32 v228, v230
	v_permlane16_swap_b32_e32 v229, v231
	global_store_dwordx4 v[236:237], v[228:231], off
	s_nop 1
	v_mov_b32_e32 v245, v16
	v_lshl_add_u64 v[238:239], v[18:19], 0, v[204:205]
	s_nop 0
	v_permlane16_swap_b32_e32 v244, v245
	global_store_dwordx2 v[238:239], v[244:245], off
	s_nop 0
	v_mul_f32_e32 v10, v7, v7
	v_mul_f32_e32 v11, v9, v9
	v_add_f32_e32 v24, v24, v26
	v_add_f32_e32 v14, v14, v15
	v_fmac_f32_e32 v10, v6, v6
	v_fmac_f32_e32 v11, v8, v8
	v_add_f32_e32 v14, v24, v14
	v_add_f32_e32 v10, v10, v11
	v_mov_b32_e32 v12, v1
	global_store_dwordx4 v[20:21], v[6:9], off offset:512
	v_cvt_pk_fp8_f32 v12, v6, v7
	v_add_f32_e32 v13, v14, v10
	v_cvt_pk_bf16_f32 v10, v6, v7
	v_pk_add_f32 v[6:7], v[4:5], v[68:69]
	v_pk_add_f32 v[4:5], v[2:3], v[66:67]
	v_mul_f32_e32 v3, v7, v7
	v_mul_f32_e32 v2, v5, v5
	v_fmac_f32_e32 v2, v4, v4
	v_fmac_f32_e32 v3, v6, v6
	v_add_f32_e32 v2, v2, v3
	v_add_f32_e32 v2, v13, v2
	ds_bpermute_b32 v3, v242, v2
	v_cvt_pk_bf16_f32 v11, v8, v9
	v_cvt_pk_fp8_f32 v12, v8, v9 op_sel:[0,0,1]
	v_mov_b32_e32 v8, v1
	v_cvt_pk_fp8_f32 v8, v4, v5
	s_waitcnt lgkmcnt(0)
	v_add_f32_e32 v2, v2, v3
	ds_bpermute_b32 v3, v241, v2
	v_mov_b32_e32 v232, v10
	v_mov_b32_e32 v233, v11
	v_mov_b32_e32 v246, v12
	global_store_dwordx4 v[20:21], v[4:7], off offset:576
	v_cvt_pk_fp8_f32 v8, v6, v7 op_sel:[0,0,1]
	s_nop 0
	v_cvt_pk_bf16_f32 v4, v4, v5
	v_cvt_pk_bf16_f32 v5, v6, v7
	v_mov_b32_e32 v234, v4
	v_mov_b32_e32 v235, v5
	v_lshl_add_u64 v[236:237], v[22:23], 0, v[202:203]
	s_nop 0
	v_permlane16_swap_b32_e32 v232, v234
	v_permlane16_swap_b32_e32 v233, v235
	global_store_dwordx4 v[236:237], v[232:235], off offset:256
	s_nop 1
	v_mov_b32_e32 v247, v8
	v_lshl_add_u64 v[238:239], v[18:19], 0, v[204:205]
	s_nop 0
	v_permlane16_swap_b32_e32 v246, v247
	global_store_dwordx2 v[238:239], v[246:247], off offset:128
	s_nop 0
	s_and_saveexec_b64 s[60:61], vcc
	s_cbranch_execz .LBB0_432
	v_lshlrev_b32_e32 v4, 5, v122
	v_ashrrev_i32_e32 v5, 31, v4
	v_lshl_add_u64 v[4:5], v[4:5], 2, s[58:59]
	s_waitcnt lgkmcnt(0)
	v_add_f32_e32 v2, v2, v3
	global_store_dword v[4:5], v2, off
